# attention fast loop: iteration seam trimmed (loop-control SALU in the last PV gaps, address SALU behind the first QK MFMA, last PV gap empty), deferred exps spread evenly over the four c0 QK gaps
# speedup vs baseline: 1.3566x; 1.0010x over previous
; __device__ __forceinline__ unsigned pk2(float lo, float hi) { f32x2_t v = {lo, hi}; bf16x2_t b = __builtin_convertvector(v, bf16x2_t); return __builtin_bit_cast(unsigned, b); }
; __device__ __forceinline__ void att_qs(bf16x8 (&pn)[4], f32x16 (&o)[4], f32x16& osum, f32x16& negm, const bf16x8 (&qf)[4], float& m_hat, ...
;     ...
;     kf[0] = ATT_KREAD(0); kf[1] = ATT_KREAD(1); kf[2] = ATT_KREAD(2); kf[3] = ATT_KREAD(3);
;     __builtin_amdgcn_sched_barrier(0);
; #pragma unroll
;     for (int i = 0; i < 8; ++i) {
;         if (i == 0) c0 = __builtin_amdgcn_mfma_f32_32x32x16_bf16(kf[0], qf[0], negm, 0, 0, 0);
;         else if (i == 1) c1 = __builtin_amdgcn_mfma_f32_32x32x16_bf16(kf[1], qf[0], negm, 0, 0, 0);
;         else if ((i & 1) == 0) c0 = __builtin_amdgcn_mfma_f32_32x32x16_bf16(kf[i & 3], qf[i >> 1], c0, 0, 0, 0);
;         else c1 = __builtin_amdgcn_mfma_f32_32x32x16_bf16(kf[i & 3], qf[i >> 1], c1, 0, 0, 0);
;         if (i + 4 < 8) kf[i & 3] = ATT_KREAD(i + 4);
;         __builtin_amdgcn_sched_barrier(0);
;     }
;     ...
;     unsigned paw[16];
; #pragma unroll
;     for (int g = 0; g < 8; ++g) { const int b = (4 * g) & 15;
;         const float v0 = __builtin_amdgcn_exp2f(g < 4 ? c0[b] : c1[b]), v1 = __builtin_amdgcn_exp2f(g < 4 ? c0[b + 1] : c1[b + 1]);
;         const float v2 = __builtin_amdgcn_exp2f(g < 4 ? c0[b + 2] : c1[b + 2]), v3 = __builtin_amdgcn_exp2f(g < 4 ? c0[b + 3] : c1[b + 3]);
;         paw[2 * g] = pk2(v0, v1); paw[2 * g + 1] = pk2(v2, v3); }
; #pragma unroll
;     for (int k = 0; k < 4; ++k) { u32x4 w; w.x = paw[4 * k]; w.y = paw[4 * k + 1]; w.z = paw[4 * k + 2]; w.w = paw[4 * k + 3]; pn[k] = __builtin_bit_cast(bf16x8, w); }
.Latt_fast_top:
	s_waitcnt lgkmcnt(3)
	v_mfma_f32_32x32x16_bf16 v[226:241], v[128:131], v[146:149], v[98:113]
	ds_read_b128 v[128:131], v132 offset:512
	v_exp_f32_e32 v2, v2
	v_exp_f32_e32 v3, v3
	v_add_f32_e32 v243, v243, v2
	v_exp_f32_e32 v4, v4
	v_add_f32_e32 v244, v244, v3
	v_exp_f32_e32 v5, v5
	v_add_f32_e32 v242, v242, v4
	v_cvt_pk_bf16_f32 v124, v2, v3
	v_add_f32_e32 v245, v245, v5
	v_exp_f32_e32 v6, v6
	s_waitcnt lgkmcnt(3)
	v_mfma_f32_32x32x16_bf16 v[226:241], v[138:141], v[150:153], v[226:241]
	ds_read_b128 v[138:141], v132 offset:2560
	v_exp_f32_e32 v7, v7
	v_add_f32_e32 v243, v243, v6
	v_cvt_pk_bf16_f32 v125, v4, v5
	v_add_f32_e32 v244, v244, v7
	v_exp_f32_e32 v8, v8
	v_exp_f32_e32 v9, v9
	v_add_f32_e32 v242, v242, v8
	v_cvt_pk_bf16_f32 v126, v6, v7
	v_add_f32_e32 v245, v245, v9
	v_cvt_pk_bf16_f32 v127, v8, v9
	s_waitcnt lgkmcnt(3)
	v_mfma_f32_32x32x16_bf16 v[226:241], v[142:145], v[154:157], v[226:241]
	ds_read_b128 v[142:145], v132 offset:4608
	v_exp_f32_e32 v10, v10
	v_exp_f32_e32 v11, v11
	v_add_f32_e32 v243, v243, v10
	v_exp_f32_e32 v12, v12
	v_add_f32_e32 v244, v244, v11
	v_exp_f32_e32 v13, v13
	v_add_f32_e32 v242, v242, v12
	v_cvt_pk_bf16_f32 v120, v10, v11
	v_add_f32_e32 v245, v245, v13
	v_exp_f32_e32 v14, v14
	s_waitcnt lgkmcnt(3)
	v_mfma_f32_32x32x16_bf16 v[226:241], v[250:253], v[158:161], v[226:241]
	ds_read_b128 v[250:253], v132 offset:6656
	s_add_i32 s10, s57, 0xffff4000
	s_and_b32 s10, s10, 0xc000
	v_add_u32_e32 v133, s10, v185
	v_exp_f32_e32 v15, v15
	v_add_f32_e32 v243, v243, v14
	v_cvt_pk_bf16_f32 v121, v12, v13
	v_add_f32_e32 v244, v244, v15
	v_exp_f32_e32 v16, v16
	v_exp_f32_e32 v17, v17
	v_add_f32_e32 v242, v242, v16
	v_cvt_pk_bf16_f32 v122, v14, v15
	v_add_f32_e32 v245, v245, v17
	v_cvt_pk_bf16_f32 v123, v16, v17
	s_waitcnt lgkmcnt(3)
	v_mfma_f32_32x32x16_bf16 v[2:17], v[128:131], v[146:149], v[98:113]
	ds_read_b64_tr_b16 v[128:129], v133
	ds_read_b64_tr_b16 v[130:131], v133 offset:512
	s_add_i32 s9, s56, 2
	s_min_u32 s9, s9, s52
	s_lshl_b32 s58, s9, 14
	s_and_b32 s59, s57, 0xc000
	s_add_i32 s59, s59, s53
	s_add_i32 s9, s56, 3
	s_min_u32 s9, s9, s52
	s_lshl_b32 s10, s9, 14
	s_mov_b32 s11, 0
	s_add_u32 s10, s98, s10
	s_addc_u32 s11, s99, 0
	s_add_i32 s9, s57, 0x4000
	s_and_b32 s9, s9, 0xc000
	s_add_i32 s9, s9, s53
	s_waitcnt lgkmcnt(4)
	v_mfma_f32_32x32x16_bf16 v[2:17], v[138:141], v[150:153], v[2:17]
	ds_read_b64_tr_b16 v[138:139], v133 offset:4096
	ds_read_b64_tr_b16 v[140:141], v133 offset:4608
	s_waitcnt lgkmcnt(5)
	v_mfma_f32_32x32x16_bf16 v[2:17], v[142:145], v[154:157], v[2:17]
	ds_read_b64_tr_b16 v[142:143], v133 offset:8192
	ds_read_b64_tr_b16 v[144:145], v133 offset:8704
	s_waitcnt lgkmcnt(6)
	v_mfma_f32_32x32x16_bf16 v[2:17], v[250:253], v[158:161], v[2:17]
	ds_read_b64_tr_b16 v[250:251], v133 offset:12288
	ds_read_b64_tr_b16 v[252:253], v133 offset:12800
.Latt_fast_pv:
	s_waitcnt lgkmcnt(6)
	v_mfma_f32_32x32x16_bf16 v[34:49], v[134:137], v[128:131], v[34:49]
	ds_read_b64_tr_b16 v[128:129], v133 offset:1024
	ds_read_b64_tr_b16 v[130:131], v133 offset:1536
	s_mov_b32 m0, s9
	s_nop 0
	global_load_lds_dwordx4 v166, s[10:11]
	s_waitcnt lgkmcnt(6)
	v_mfma_f32_32x32x16_bf16 v[50:65], v[134:137], v[138:141], v[50:65]
	ds_read_b64_tr_b16 v[138:139], v133 offset:5120
	ds_read_b64_tr_b16 v[140:141], v133 offset:5632
	s_add_u32 s10, s10, 0x2000
	s_addc_u32 s11, s11, 0
	s_add_i32 m0, s9, 0x2000
	s_nop 0
	global_load_lds_dwordx4 v166, s[10:11]
	s_waitcnt lgkmcnt(6)
	v_mfma_f32_32x32x16_bf16 v[66:81], v[134:137], v[142:145], v[66:81]
	ds_read_b64_tr_b16 v[142:143], v133 offset:9216
	ds_read_b64_tr_b16 v[144:145], v133 offset:9728
	s_add_u32 s10, s100, s58
	s_addc_u32 s11, s101, 0
	s_add_i32 m0, s59, 0x10000
	s_nop 0
	global_load_lds_dwordx4 v166, s[10:11]
	s_waitcnt lgkmcnt(6)
	v_mfma_f32_32x32x16_bf16 v[82:97], v[134:137], v[250:253], v[82:97]
	ds_read_b64_tr_b16 v[250:251], v133 offset:13312
	ds_read_b64_tr_b16 v[252:253], v133 offset:13824
	s_add_u32 s10, s10, 0x2000
	s_addc_u32 s11, s11, 0
	s_add_i32 m0, s59, 0x12000
	s_nop 0
	global_load_lds_dwordx4 v166, s[10:11]
	s_waitcnt lgkmcnt(6)
	v_mfma_f32_32x32x16_bf16 v[34:49], v[114:117], v[128:131], v[34:49]
	ds_read_b64_tr_b16 v[128:129], v133 offset:2048
	ds_read_b64_tr_b16 v[130:131], v133 offset:2560
	v_max3_f32 v0, v226, v227, v228
	v_max3_f32 v225, v2, v3, v4
	v_max3_f32 v0, v0, v229, v230
	v_max3_f32 v225, v225, v5, v6
	s_waitcnt lgkmcnt(6)
	v_mfma_f32_32x32x16_bf16 v[50:65], v[114:117], v[138:141], v[50:65]
	ds_read_b64_tr_b16 v[138:139], v133 offset:6144
	ds_read_b64_tr_b16 v[140:141], v133 offset:6656
	v_max3_f32 v0, v0, v231, v232
	v_max3_f32 v225, v225, v7, v8
	v_max3_f32 v0, v0, v233, v234
	v_max3_f32 v225, v225, v9, v10
	s_waitcnt lgkmcnt(6)
	v_mfma_f32_32x32x16_bf16 v[66:81], v[114:117], v[142:145], v[66:81]
	ds_read_b64_tr_b16 v[142:143], v133 offset:10240
	ds_read_b64_tr_b16 v[144:145], v133 offset:10752
	v_max3_f32 v0, v0, v235, v236
	v_max3_f32 v225, v225, v11, v12
	v_max3_f32 v0, v0, v237, v238
	v_max3_f32 v225, v225, v13, v14
	s_waitcnt lgkmcnt(6)
	v_mfma_f32_32x32x16_bf16 v[82:97], v[114:117], v[250:253], v[82:97]
	ds_read_b64_tr_b16 v[250:251], v133 offset:14336
	ds_read_b64_tr_b16 v[252:253], v133 offset:14848
	v_max3_f32 v0, v0, v239, v240
	v_max3_f32 v225, v225, v15, v16
	v_max3_f32 v0, v0, v225, v241
	v_max3_f32 v0, v0, v17, v17
	v_cmp_lt_f32_e32 vcc, s36, v0
	s_cbranch_vccnz .Latt_fast_rescale
; #define LAS __attribute__((address_space(3)))
; __device__ __forceinline__ unsigned pk2(float lo, float hi) { f32x2_t v = {lo, hi}; bf16x2_t b = __builtin_convertvector(v, bf16x2_t); return __builtin_bit_cast(unsigned, b); }
; #define ATT_VREADK(ks) do { _Pragma("unroll") for (int d_ = 0; d_ < 4; ++d_) { vl[(ks) & 1][d_] = vtr(vb + d_ * 4096 + (ks) * 1024); vh[(ks) & 1][d_] = vtr(vb + d_ * 4096 + (ks) * 1024 + 512); } } while (0)
; __device__ __forceinline__ void att_qs(bf16x8 (&pn)[4], f32x16 (&o)[4], f32x16& osum, f32x16& negm, const bf16x8 (&qf)[4], float& m_hat, ...
;     ...
;     unsigned paw[16];
; #pragma unroll
;     for (int g = 0; g < 8; ++g) { const int b = (4 * g) & 15;
;         const float v0 = __builtin_amdgcn_exp2f(g < 4 ? c0[b] : c1[b]), v1 = __builtin_amdgcn_exp2f(g < 4 ? c0[b + 1] : c1[b + 1]);
;         const float v2 = __builtin_amdgcn_exp2f(g < 4 ? c0[b + 2] : c1[b + 2]), v3 = __builtin_amdgcn_exp2f(g < 4 ? c0[b + 3] : c1[b + 3]);
;         paw[2 * g] = pk2(v0, v1); paw[2 * g + 1] = pk2(v2, v3); }
; #pragma unroll
;     for (int k = 0; k < 4; ++k) { u32x4 w; w.x = paw[4 * k]; w.y = paw[4 * k + 1]; w.z = paw[4 * k + 2]; w.w = paw[4 * k + 3]; pn[k] = __builtin_bit_cast(bf16x8, w); }
;     __builtin_amdgcn_s_setprio(0);
; }
; __device__ __forceinline__ void att_pv(const bf16x8 (&pp)[4], f32x16 (&o)[4], f32x16& osum, const LAS unsigned char* vb) {
;     s16x4 vl[2][4], vh[2][4];
;     ...
;     const bf16x8 ones = (bf16x8){0x3F80, 0x3F80, 0x3F80, 0x3F80, 0x3F80, 0x3F80, 0x3F80, 0x3F80};
;     ATT_VREADK(0);
; #pragma unroll
;     for (int ks = 0; ks < 4; ++ks) {
;         if (ks + 1 < 4) ATT_VREADK(ks + 1);
;         osum = __builtin_amdgcn_mfma_f32_32x32x16_bf16(pp[ks], ones, osum, 0, 0, 0);
; #pragma unroll
;         for (int d = 0; d < 4; ++d) { const int bk = ks & 1;
;             const bf16x8 vf = (bf16x8){vl[bk][d][0], vl[bk][d][1], vl[bk][d][2], vl[bk][d][3], vh[bk][d][0], vh[bk][d][1], vh[bk][d][2], vh[bk][d][3]};
;             o[d] = __builtin_amdgcn_mfma_f32_32x32x16_bf16(pp[ks], vf, o[d], 0, 0, 0); }
;     }
	s_waitcnt lgkmcnt(6)
	v_mfma_f32_32x32x16_bf16 v[34:49], v[124:127], v[128:131], v[34:49]
	ds_read_b64_tr_b16 v[128:129], v133 offset:3072
	ds_read_b64_tr_b16 v[130:131], v133 offset:3584
	v_exp_f32_e32 v226, v226
	v_exp_f32_e32 v227, v227
	v_add_f32_e32 v243, v243, v226
	v_exp_f32_e32 v228, v228
	v_add_f32_e32 v244, v244, v227
	s_waitcnt lgkmcnt(6)
	v_mfma_f32_32x32x16_bf16 v[50:65], v[124:127], v[138:141], v[50:65]
	ds_read_b64_tr_b16 v[138:139], v133 offset:7168
	ds_read_b64_tr_b16 v[140:141], v133 offset:7680
	v_exp_f32_e32 v229, v229
	v_add_f32_e32 v242, v242, v228
	v_cvt_pk_bf16_f32 v134, v226, v227
	v_add_f32_e32 v245, v245, v229
	v_exp_f32_e32 v230, v230
	s_waitcnt lgkmcnt(6)
	v_mfma_f32_32x32x16_bf16 v[66:81], v[124:127], v[142:145], v[66:81]
	ds_read_b64_tr_b16 v[142:143], v133 offset:11264
	ds_read_b64_tr_b16 v[144:145], v133 offset:11776
	v_exp_f32_e32 v231, v231
	v_add_f32_e32 v243, v243, v230
	v_cvt_pk_bf16_f32 v135, v228, v229
	v_add_f32_e32 v244, v244, v231
	v_exp_f32_e32 v232, v232
	s_waitcnt lgkmcnt(6)
	v_mfma_f32_32x32x16_bf16 v[82:97], v[124:127], v[250:253], v[82:97]
	ds_read_b64_tr_b16 v[250:251], v133 offset:15360
	ds_read_b64_tr_b16 v[252:253], v133 offset:15872
	v_exp_f32_e32 v233, v233
	v_add_f32_e32 v242, v242, v232
	v_cvt_pk_bf16_f32 v136, v230, v231
	v_add_f32_e32 v245, v245, v233
	v_cvt_pk_bf16_f32 v137, v232, v233
	s_waitcnt lgkmcnt(6)
	v_mfma_f32_32x32x16_bf16 v[34:49], v[120:123], v[128:131], v[34:49]
	s_add_i32 s9, s57, 0xffffc000
	s_and_b32 s9, s9, 0xc000
	v_add_u32_e32 v132, s9, v177
	ds_read_b128 v[128:131], v132
	v_exp_f32_e32 v234, v234
	v_exp_f32_e32 v235, v235
	v_add_f32_e32 v243, v243, v234
	v_exp_f32_e32 v236, v236
	v_add_f32_e32 v244, v244, v235
	v_exp_f32_e32 v237, v237
	v_add_f32_e32 v242, v242, v236
	s_waitcnt lgkmcnt(5)
	v_mfma_f32_32x32x16_bf16 v[50:65], v[120:123], v[138:141], v[50:65]
	ds_read_b128 v[138:141], v132 offset:2048
	s_add_i32 s56, s56, 1
	s_addk_i32 s57, 0x4000
	s_add_i32 s55, s55, 64
	s_cmp_lg_u32 s50, s56
	s_cselect_b32 s16, 1, 0
	s_cmp_le_u32 s56, s54
	s_cselect_b32 s16, s16, 0
	s_cmpk_lt_i32 s55, 0xffa6
	s_cselect_b32 s16, s16, 0
	v_cvt_pk_bf16_f32 v114, v234, v235
	v_add_f32_e32 v245, v245, v237
	v_exp_f32_e32 v238, v238
	v_exp_f32_e32 v239, v239
	v_add_f32_e32 v243, v243, v238
	v_cvt_pk_bf16_f32 v115, v236, v237
	v_add_f32_e32 v244, v244, v239
	s_waitcnt lgkmcnt(4)
	v_mfma_f32_32x32x16_bf16 v[66:81], v[120:123], v[142:145], v[66:81]
	ds_read_b128 v[142:145], v132 offset:4096
	v_exp_f32_e32 v240, v240
	v_exp_f32_e32 v241, v241
	v_add_f32_e32 v242, v242, v240
	v_cvt_pk_bf16_f32 v116, v238, v239
	v_add_f32_e32 v245, v245, v241
	v_cvt_pk_bf16_f32 v117, v240, v241
	s_waitcnt lgkmcnt(3)
	v_mfma_f32_32x32x16_bf16 v[82:97], v[120:123], v[250:253], v[82:97]
	ds_read_b128 v[250:253], v132 offset:6144
.Latt_fast_end:
	s_waitcnt vmcnt(4)
	s_barrier
	s_cmp_lg_u32 s16, 0
	s_cbranch_scc1 .Latt_fast_top
.Latt_fast_exit:
	s_waitcnt lgkmcnt(0)
	v_exp_f32_e32 v2, v2
	v_exp_f32_e32 v3, v3
	v_add_f32_e32 v243, v243, v2
	v_exp_f32_e32 v4, v4
	v_add_f32_e32 v244, v244, v3
	v_exp_f32_e32 v5, v5
	v_add_f32_e32 v242, v242, v4
	v_cvt_pk_bf16_f32 v124, v2, v3
	v_add_f32_e32 v245, v245, v5
	v_exp_f32_e32 v6, v6
	v_exp_f32_e32 v7, v7
	v_add_f32_e32 v243, v243, v6
	v_cvt_pk_bf16_f32 v125, v4, v5
	v_add_f32_e32 v244, v244, v7
	v_exp_f32_e32 v8, v8
	v_exp_f32_e32 v9, v9
	v_add_f32_e32 v242, v242, v8
	v_cvt_pk_bf16_f32 v126, v6, v7
	v_add_f32_e32 v245, v245, v9
	v_cvt_pk_bf16_f32 v127, v8, v9
	v_exp_f32_e32 v10, v10
	v_exp_f32_e32 v11, v11
	v_add_f32_e32 v243, v243, v10
	v_exp_f32_e32 v12, v12
	v_add_f32_e32 v244, v244, v11
	v_exp_f32_e32 v13, v13
	v_add_f32_e32 v242, v242, v12
	v_cvt_pk_bf16_f32 v120, v10, v11
	v_add_f32_e32 v245, v245, v13
	v_exp_f32_e32 v14, v14
	v_exp_f32_e32 v15, v15
	v_add_f32_e32 v243, v243, v14
	v_cvt_pk_bf16_f32 v121, v12, v13
	v_add_f32_e32 v244, v244, v15
	v_exp_f32_e32 v16, v16
	v_exp_f32_e32 v17, v17
	v_add_f32_e32 v242, v242, v16
	v_cvt_pk_bf16_f32 v122, v14, v15
	v_add_f32_e32 v245, v245, v17
	v_cvt_pk_bf16_f32 v123, v16, v17
	s_add_i32 s10, s57, 0xffff4000
	s_and_b32 s10, s10, 0xc000
	v_add_u32_e32 v133, s10, v185
	ds_read_b64_tr_b16 v[128:129], v133
	ds_read_b64_tr_b16 v[130:131], v133 offset:512
	ds_read_b64_tr_b16 v[138:139], v133 offset:4096
	ds_read_b64_tr_b16 v[140:141], v133 offset:4608
	ds_read_b64_tr_b16 v[142:143], v133 offset:8192
	ds_read_b64_tr_b16 v[144:145], v133 offset:8704
	ds_read_b64_tr_b16 v[250:251], v133 offset:12288
	ds_read_b64_tr_b16 v[252:253], v133 offset:12800
	s_waitcnt lgkmcnt(6)
	v_mfma_f32_32x32x16_bf16 v[34:49], v[134:137], v[128:131], v[34:49]
	ds_read_b64_tr_b16 v[128:129], v133 offset:1024
	ds_read_b64_tr_b16 v[130:131], v133 offset:1536
	s_waitcnt lgkmcnt(6)
	v_mfma_f32_32x32x16_bf16 v[50:65], v[134:137], v[138:141], v[50:65]
	ds_read_b64_tr_b16 v[138:139], v133 offset:5120
	ds_read_b64_tr_b16 v[140:141], v133 offset:5632
	s_waitcnt lgkmcnt(6)
	v_mfma_f32_32x32x16_bf16 v[66:81], v[134:137], v[142:145], v[66:81]
	ds_read_b64_tr_b16 v[142:143], v133 offset:9216
	ds_read_b64_tr_b16 v[144:145], v133 offset:9728
	s_waitcnt lgkmcnt(6)
	v_mfma_f32_32x32x16_bf16 v[82:97], v[134:137], v[250:253], v[82:97]
	ds_read_b64_tr_b16 v[250:251], v133 offset:13312
	ds_read_b64_tr_b16 v[252:253], v133 offset:13824
	s_waitcnt lgkmcnt(6)
	v_mfma_f32_32x32x16_bf16 v[34:49], v[114:117], v[128:131], v[34:49]
	ds_read_b64_tr_b16 v[128:129], v133 offset:2048
	ds_read_b64_tr_b16 v[130:131], v133 offset:2560
	s_waitcnt lgkmcnt(6)
	v_mfma_f32_32x32x16_bf16 v[50:65], v[114:117], v[138:141], v[50:65]
	ds_read_b64_tr_b16 v[138:139], v133 offset:6144
	ds_read_b64_tr_b16 v[140:141], v133 offset:6656
	s_waitcnt lgkmcnt(6)
; __device__ __forceinline__ int crow(int r, int hi) { return (r & 3) + 8 * (r >> 2) + 4 * hi; }
; #define ATT_VREADK(ks) do { _Pragma("unroll") for (int d_ = 0; d_ < 4; ++d_) { vl[(ks) & 1][d_] = vtr(vb + d_ * 4096 + (ks) * 1024); vh[(ks) & 1][d_] = vtr(vb + d_ * 4096 + (ks) * 1024 + 512); } } while (0)
; __device__ __forceinline__ void att_qs(bf16x8 (&pn)[4], f32x16 (&o)[4], f32x16& osum, f32x16& negm, const bf16x8 (&qf)[4], float& m_hat, ...
;     ...
;     } else if (__any(rm > 8.0f)) {
;         const float dl = fmaxf(rm, 0.f); m_hat += dl; const float f = __builtin_amdgcn_exp2f(-dl);
; #pragma unroll
;         for (int r = 0; r < 16; ++r) { c0[r] -= dl; c1[r] -= dl; negm[r] = -m_hat; }
;         if (hi == 0) scr[i32] = f;
;         asm volatile("s_waitcnt lgkmcnt(0)" ::: "memory");
; #pragma unroll
;         for (int r = 0; r < 16; ++r) { const float fr_ = scr[crow(r, hi)]; osum[r] *= fr_;
; #pragma unroll
;             for (int d = 0; d < 4; ++d) o[d][r] *= fr_; }
;     }
; __device__ __forceinline__ void att_pv(const bf16x8 (&pp)[4], f32x16 (&o)[4], f32x16& osum, const LAS unsigned char* vb) {
;     ...
;     const bf16x8 ones = (bf16x8){0x3F80, 0x3F80, 0x3F80, 0x3F80, 0x3F80, 0x3F80, 0x3F80, 0x3F80};
;     ATT_VREADK(0);
; #pragma unroll
;     for (int ks = 0; ks < 4; ++ks) {
;         if (ks + 1 < 4) ATT_VREADK(ks + 1);
;         osum = __builtin_amdgcn_mfma_f32_32x32x16_bf16(pp[ks], ones, osum, 0, 0, 0);
; #pragma unroll
;         for (int d = 0; d < 4; ++d) { const int bk = ks & 1;
;             const bf16x8 vf = (bf16x8){vl[bk][d][0], vl[bk][d][1], vl[bk][d][2], vl[bk][d][3], vh[bk][d][0], vh[bk][d][1], vh[bk][d][2], vh[bk][d][3]};
;             o[d] = __builtin_amdgcn_mfma_f32_32x32x16_bf16(pp[ks], vf, o[d], 0, 0, 0); }
;     }
	v_mfma_f32_32x32x16_bf16 v[66:81], v[114:117], v[142:145], v[66:81]
	ds_read_b64_tr_b16 v[142:143], v133 offset:10240
	ds_read_b64_tr_b16 v[144:145], v133 offset:10752
	s_waitcnt lgkmcnt(6)
	v_mfma_f32_32x32x16_bf16 v[82:97], v[114:117], v[250:253], v[82:97]
	ds_read_b64_tr_b16 v[250:251], v133 offset:14336
	ds_read_b64_tr_b16 v[252:253], v133 offset:14848
	s_waitcnt lgkmcnt(6)
	v_mfma_f32_32x32x16_bf16 v[34:49], v[124:127], v[128:131], v[34:49]
	ds_read_b64_tr_b16 v[128:129], v133 offset:3072
	ds_read_b64_tr_b16 v[130:131], v133 offset:3584
	s_waitcnt lgkmcnt(6)
	v_mfma_f32_32x32x16_bf16 v[50:65], v[124:127], v[138:141], v[50:65]
	ds_read_b64_tr_b16 v[138:139], v133 offset:7168
	ds_read_b64_tr_b16 v[140:141], v133 offset:7680
	s_waitcnt lgkmcnt(6)
	v_mfma_f32_32x32x16_bf16 v[66:81], v[124:127], v[142:145], v[66:81]
	ds_read_b64_tr_b16 v[142:143], v133 offset:11264
	ds_read_b64_tr_b16 v[144:145], v133 offset:11776
	s_waitcnt lgkmcnt(6)
	v_mfma_f32_32x32x16_bf16 v[82:97], v[124:127], v[250:253], v[82:97]
	ds_read_b64_tr_b16 v[250:251], v133 offset:15360
	ds_read_b64_tr_b16 v[252:253], v133 offset:15872
	s_waitcnt lgkmcnt(6)
	v_mfma_f32_32x32x16_bf16 v[34:49], v[120:123], v[128:131], v[34:49]
	s_waitcnt lgkmcnt(4)
	v_mfma_f32_32x32x16_bf16 v[50:65], v[120:123], v[138:141], v[50:65]
	s_waitcnt lgkmcnt(2)
	v_mfma_f32_32x32x16_bf16 v[66:81], v[120:123], v[142:145], v[66:81]
	s_waitcnt lgkmcnt(0)
	v_mfma_f32_32x32x16_bf16 v[82:97], v[120:123], v[250:253], v[82:97]
	v_add_f32_e32 v243, v243, v242
	v_add_f32_e32 v244, v244, v245
	v_add_f32_e32 v243, v243, v244
	v_mov_b32_e32 v244, v243
	s_nop 1
	v_permlane32_swap_b32_e32 v243, v244
	v_add_f32_e32 v243, v243, v244
	s_and_saveexec_b64 s[10:11], s[6:7]
	ds_write_b32 v224, v243
	s_or_b64 exec, exec, s[10:11]
	s_waitcnt lgkmcnt(0)
	v_add_u32_e32 v132, s51, v187
	ds_read_b128 v[128:131], v132
	ds_read_b128 v[138:141], v132 offset:32
	ds_read_b128 v[142:145], v132 offset:64
	ds_read_b128 v[250:253], v132 offset:96
	v_mov_b32_e32 v17, v248
	v_mov_b32_e32 v16, v118
	s_waitcnt lgkmcnt(0)
	v_add_f32_e32 v18, v18, v128
	v_add_f32_e32 v19, v19, v129
	v_add_f32_e32 v20, v20, v130
	v_add_f32_e32 v21, v21, v131
	v_add_f32_e32 v22, v22, v138
	v_add_f32_e32 v23, v23, v139
	v_add_f32_e32 v24, v24, v140
	v_add_f32_e32 v25, v25, v141
	v_add_f32_e32 v26, v26, v142
	v_add_f32_e32 v27, v27, v143
	v_add_f32_e32 v28, v28, v144
	v_add_f32_e32 v29, v29, v145
	v_add_f32_e32 v30, v30, v250
	v_add_f32_e32 v31, v31, v251
	v_add_f32_e32 v32, v32, v252
	v_add_f32_e32 v33, v33, v253
	s_cmp_eq_u32 s50, s56
	s_cbranch_scc1 .LBB0_695
	s_branch .LBB0_686
.Latt_fast_rescale:
	s_waitcnt lgkmcnt(0)
	v_mfma_f32_32x32x16_bf16 v[34:49], v[124:127], v[128:131], v[34:49]
	v_mfma_f32_32x32x16_bf16 v[50:65], v[124:127], v[138:141], v[50:65]
	v_mfma_f32_32x32x16_bf16 v[66:81], v[124:127], v[142:145], v[66:81]
	v_mfma_f32_32x32x16_bf16 v[82:97], v[124:127], v[250:253], v[82:97]
	ds_read_b64_tr_b16 v[128:129], v133 offset:3072
	ds_read_b64_tr_b16 v[130:131], v133 offset:3584
	ds_read_b64_tr_b16 v[138:139], v133 offset:7168
	ds_read_b64_tr_b16 v[140:141], v133 offset:7680
	ds_read_b64_tr_b16 v[142:143], v133 offset:11264
	ds_read_b64_tr_b16 v[144:145], v133 offset:11776
	ds_read_b64_tr_b16 v[250:251], v133 offset:15360
	ds_read_b64_tr_b16 v[252:253], v133 offset:15872
	s_waitcnt lgkmcnt(0)
	v_mfma_f32_32x32x16_bf16 v[34:49], v[120:123], v[128:131], v[34:49]
	v_mfma_f32_32x32x16_bf16 v[50:65], v[120:123], v[138:141], v[50:65]
	v_mfma_f32_32x32x16_bf16 v[66:81], v[120:123], v[142:145], v[66:81]
	v_mfma_f32_32x32x16_bf16 v[82:97], v[120:123], v[250:253], v[82:97]
	s_nop 15
	v_mov_b32_e32 v225, v0
	s_nop 1
	v_permlane32_swap_b32_e32 v0, v225
	v_max_f32_e32 v0, v0, v225
	v_max_f32_e32 v0, 0, v0
	v_add_f32_e32 v248, v248, v0
	v_exp_f32_e64 v225, -v0
	s_and_saveexec_b64 s[10:11], s[6:7]
	ds_write_b32 v224, v225
	s_or_b64 exec, exec, s[10:11]
	v_mul_f32_e32 v243, v243, v225
	v_mul_f32_e32 v244, v244, v225
	v_mul_f32_e32 v242, v242, v225
	v_mul_f32_e32 v245, v245, v225
	s_waitcnt lgkmcnt(0)
	v_add_u32_e32 v132, s51, v187
	ds_read_b128 v[128:131], v132
	ds_read_b128 v[138:141], v132 offset:32
	ds_read_b128 v[142:145], v132 offset:64
	ds_read_b128 v[250:253], v132 offset:96
	v_sub_f32_e32 v226, v226, v0
	v_sub_f32_e32 v227, v227, v0
	v_sub_f32_e32 v228, v228, v0
	v_sub_f32_e32 v229, v229, v0
	v_sub_f32_e32 v230, v230, v0
	v_sub_f32_e32 v231, v231, v0
	v_sub_f32_e32 v232, v232, v0
	v_sub_f32_e32 v233, v233, v0
	v_sub_f32_e32 v234, v234, v0
	v_sub_f32_e32 v235, v235, v0
	v_sub_f32_e32 v236, v236, v0
	v_sub_f32_e32 v237, v237, v0
	v_sub_f32_e32 v238, v238, v0
	v_sub_f32_e32 v239, v239, v0
	v_sub_f32_e32 v240, v240, v0
	v_sub_f32_e32 v241, v241, v0
	v_sub_f32_e32 v2, v2, v0
	v_sub_f32_e32 v3, v3, v0
	v_sub_f32_e32 v4, v4, v0
	v_sub_f32_e32 v5, v5, v0
	v_sub_f32_e32 v6, v6, v0
	v_sub_f32_e32 v7, v7, v0
	v_sub_f32_e32 v8, v8, v0
	v_sub_f32_e32 v9, v9, v0
	v_sub_f32_e32 v10, v10, v0
	v_sub_f32_e32 v11, v11, v0
	v_sub_f32_e32 v12, v12, v0
	v_sub_f32_e32 v13, v13, v0
	v_sub_f32_e32 v14, v14, v0
	v_sub_f32_e32 v15, v15, v0
	v_sub_f32_e32 v16, v16, v0
	v_sub_f32_e32 v17, v17, v0
	v_xor_b32_e32 v98, 0x80000000, v248
	v_mov_b32_e32 v99, v98
	v_mov_b32_e32 v100, v98
	v_mov_b32_e32 v101, v98
	v_mov_b32_e32 v102, v98
	v_mov_b32_e32 v103, v98
	v_mov_b32_e32 v104, v98
	v_mov_b32_e32 v105, v98
	v_mov_b32_e32 v106, v98
	v_mov_b32_e32 v107, v98
	v_mov_b32_e32 v108, v98
	v_mov_b32_e32 v109, v98
	v_mov_b32_e32 v110, v98
	v_mov_b32_e32 v111, v98
	v_mov_b32_e32 v112, v98
	v_mov_b32_e32 v113, v98
	s_waitcnt lgkmcnt(0)
; __device__ __forceinline__ unsigned pk2(float lo, float hi) { f32x2_t v = {lo, hi}; bf16x2_t b = __builtin_convertvector(v, bf16x2_t); return __builtin_bit_cast(unsigned, b); }
; __device__ __forceinline__ int crow(int r, int hi) { return (r & 3) + 8 * (r >> 2) + 4 * hi; }
; __device__ __forceinline__ void att_qs(bf16x8 (&pn)[4], f32x16 (&o)[4], f32x16& osum, f32x16& negm, const bf16x8 (&qf)[4], float& m_hat, ...
;     ...
; #pragma unroll
;         for (int r = 0; r < 16; ++r) { const float fr_ = scr[crow(r, hi)]; osum[r] *= fr_;
; #pragma unroll
;             for (int d = 0; d < 4; ++d) o[d][r] *= fr_; }
;     }
;     unsigned paw[16];
; #pragma unroll
;     for (int g = 0; g < 8; ++g) { const int b = (4 * g) & 15;
;         const float v0 = __builtin_amdgcn_exp2f(g < 4 ? c0[b] : c1[b]), v1 = __builtin_amdgcn_exp2f(g < 4 ? c0[b + 1] : c1[b + 1]);
;         const float v2 = __builtin_amdgcn_exp2f(g < 4 ? c0[b + 2] : c1[b + 2]), v3 = __builtin_amdgcn_exp2f(g < 4 ? c0[b + 3] : c1[b + 3]);
;         paw[2 * g] = pk2(v0, v1); paw[2 * g + 1] = pk2(v2, v3); }
; #pragma unroll
;     for (int k = 0; k < 4; ++k) { u32x4 w; w.x = paw[4 * k]; w.y = paw[4 * k + 1]; w.z = paw[4 * k + 2]; w.w = paw[4 * k + 3]; pn[k] = __builtin_bit_cast(bf16x8, w); }
	v_mul_f32_e32 v18, v18, v128
	v_mul_f32_e32 v34, v34, v128
	v_mul_f32_e32 v50, v50, v128
	v_mul_f32_e32 v66, v66, v128
	v_mul_f32_e32 v82, v82, v128
	v_mul_f32_e32 v19, v19, v129
	v_mul_f32_e32 v35, v35, v129
	v_mul_f32_e32 v51, v51, v129
	v_mul_f32_e32 v67, v67, v129
	v_mul_f32_e32 v83, v83, v129
	v_mul_f32_e32 v20, v20, v130
	v_mul_f32_e32 v36, v36, v130
	v_mul_f32_e32 v52, v52, v130
	v_mul_f32_e32 v68, v68, v130
	v_mul_f32_e32 v84, v84, v130
	v_mul_f32_e32 v21, v21, v131
	v_mul_f32_e32 v37, v37, v131
	v_mul_f32_e32 v53, v53, v131
	v_mul_f32_e32 v69, v69, v131
	v_mul_f32_e32 v85, v85, v131
	v_mul_f32_e32 v22, v22, v138
	v_mul_f32_e32 v38, v38, v138
	v_mul_f32_e32 v54, v54, v138
	v_mul_f32_e32 v70, v70, v138
	v_mul_f32_e32 v86, v86, v138
	v_mul_f32_e32 v23, v23, v139
	v_mul_f32_e32 v39, v39, v139
	v_mul_f32_e32 v55, v55, v139
	v_mul_f32_e32 v71, v71, v139
	v_mul_f32_e32 v87, v87, v139
	v_mul_f32_e32 v24, v24, v140
	v_mul_f32_e32 v40, v40, v140
	v_mul_f32_e32 v56, v56, v140
	v_mul_f32_e32 v72, v72, v140
	v_mul_f32_e32 v88, v88, v140
	v_mul_f32_e32 v25, v25, v141
	v_mul_f32_e32 v41, v41, v141
	v_mul_f32_e32 v57, v57, v141
	v_mul_f32_e32 v73, v73, v141
	v_mul_f32_e32 v89, v89, v141
	v_mul_f32_e32 v26, v26, v142
	v_mul_f32_e32 v42, v42, v142
	v_mul_f32_e32 v58, v58, v142
	v_mul_f32_e32 v74, v74, v142
	v_mul_f32_e32 v90, v90, v142
	v_mul_f32_e32 v27, v27, v143
	v_mul_f32_e32 v43, v43, v143
	v_mul_f32_e32 v59, v59, v143
	v_mul_f32_e32 v75, v75, v143
	v_mul_f32_e32 v91, v91, v143
	v_mul_f32_e32 v28, v28, v144
	v_mul_f32_e32 v44, v44, v144
	v_mul_f32_e32 v60, v60, v144
	v_mul_f32_e32 v76, v76, v144
	v_mul_f32_e32 v92, v92, v144
	v_mul_f32_e32 v29, v29, v145
	v_mul_f32_e32 v45, v45, v145
	v_mul_f32_e32 v61, v61, v145
	v_mul_f32_e32 v77, v77, v145
	v_mul_f32_e32 v93, v93, v145
	v_mul_f32_e32 v30, v30, v250
	v_mul_f32_e32 v46, v46, v250
	v_mul_f32_e32 v62, v62, v250
	v_mul_f32_e32 v78, v78, v250
	v_mul_f32_e32 v94, v94, v250
	v_mul_f32_e32 v31, v31, v251
	v_mul_f32_e32 v47, v47, v251
	v_mul_f32_e32 v63, v63, v251
	v_mul_f32_e32 v79, v79, v251
	v_mul_f32_e32 v95, v95, v251
	v_mul_f32_e32 v32, v32, v252
	v_mul_f32_e32 v48, v48, v252
	v_mul_f32_e32 v64, v64, v252
	v_mul_f32_e32 v80, v80, v252
	v_mul_f32_e32 v96, v96, v252
	v_mul_f32_e32 v33, v33, v253
	v_mul_f32_e32 v49, v49, v253
	v_mul_f32_e32 v65, v65, v253
	v_mul_f32_e32 v81, v81, v253
	v_mul_f32_e32 v97, v97, v253
	v_exp_f32_e32 v226, v226
	v_exp_f32_e32 v227, v227
	v_add_f32_e32 v243, v243, v226
	v_exp_f32_e32 v228, v228
	v_add_f32_e32 v244, v244, v227
	v_exp_f32_e32 v229, v229
	v_add_f32_e32 v242, v242, v228
	v_cvt_pk_bf16_f32 v134, v226, v227
	v_add_f32_e32 v245, v245, v229
	v_exp_f32_e32 v230, v230
	v_exp_f32_e32 v231, v231
	v_add_f32_e32 v243, v243, v230
	v_cvt_pk_bf16_f32 v135, v228, v229
	v_add_f32_e32 v244, v244, v231
	v_exp_f32_e32 v232, v232
	v_exp_f32_e32 v233, v233
	v_add_f32_e32 v242, v242, v232
	v_cvt_pk_bf16_f32 v136, v230, v231
	v_add_f32_e32 v245, v245, v233
	v_cvt_pk_bf16_f32 v137, v232, v233
	v_exp_f32_e32 v234, v234
	v_exp_f32_e32 v235, v235
	v_add_f32_e32 v243, v243, v234
	v_exp_f32_e32 v236, v236
	v_add_f32_e32 v244, v244, v235
	v_exp_f32_e32 v237, v237
	v_add_f32_e32 v242, v242, v236
	v_cvt_pk_bf16_f32 v114, v234, v235
	v_add_f32_e32 v245, v245, v237
	v_exp_f32_e32 v238, v238
	v_exp_f32_e32 v239, v239
	v_add_f32_e32 v243, v243, v238
	v_cvt_pk_bf16_f32 v115, v236, v237
	v_add_f32_e32 v244, v244, v239
	v_exp_f32_e32 v240, v240
	v_exp_f32_e32 v241, v241
	v_add_f32_e32 v242, v242, v240
	v_cvt_pk_bf16_f32 v116, v238, v239
	v_add_f32_e32 v245, v245, v241
	v_cvt_pk_bf16_f32 v117, v240, v241
	s_waitcnt lgkmcnt(0)
	s_add_i32 s9, s57, 0xffffc000
	s_and_b32 s9, s9, 0xc000
	v_add_u32_e32 v132, s9, v177
	ds_read_b128 v[128:131], v132
	ds_read_b128 v[138:141], v132 offset:2048
	ds_read_b128 v[142:145], v132 offset:4096
	ds_read_b128 v[250:253], v132 offset:6144
	s_add_i32 s56, s56, 1
	s_addk_i32 s57, 0x4000
	s_add_i32 s55, s55, 64
	s_cmp_lg_u32 s50, s56
	s_cselect_b32 s16, 1, 0
	s_cmp_le_u32 s56, s54
	s_cselect_b32 s16, s16, 0
	s_cmpk_lt_i32 s55, 0xffa6
	s_cselect_b32 s16, s16, 0
	s_branch .Latt_fast_end
